# first grid-barrier scan of the 16 per-XCD counters issued as 16 loads in flight instead of 16 serialized round trips, on top of v81
# baseline (speedup 1.0000x reference)
; DI unsigned xb_ld(unsigned* p)              { return __hip_atomic_load(p, __ATOMIC_RELAXED, __HIP_MEMORY_SCOPE_AGENT); }
; DI void xcd_barrier_complete(unsigned* bar, unsigned x, unsigned& nloc, unsigned& nx) {
;     const unsigned G = gridDim.x;
;     unsigned sum, cnt, mine, sp = 0u;
;     for (;;) {
;         sum = 0u; cnt = 0u; mine = 0u;
; #pragma unroll
;         for (unsigned j = 0; j < 16; ++j) { const unsigned c = xb_ld(&bar[XB_XCNT(j)]); sum += c; cnt += (c > 0u) ? 1u : 0u; mine = (j == x) ? c : mine; }
;         if (sum == G) break;
;         __builtin_amdgcn_s_sleep(1);
;         if ((++sp & 255u) == 0u) { if (xb_ld(&bar[XB_TMO])) break; if (sp > XB_SPIN_CAP) { atomicAdd(&bar[XB_TMO], 1u); break; } }
;     }
;     nloc = mine > 0u ? mine : 1u; nx = cnt > 0u ? cnt : 1u;
; }
.LBB0_98:
	v_readlane_b32 s4, v251, 3
	s_waitcnt lgkmcnt(0)
	v_readlane_b32 s2, v252, 4
	v_readlane_b32 s3, v252, 5
	s_nop 4
	global_load_dword v0, v113, s[2:3] sc1
	v_readlane_b32 s2, v252, 6
	v_readlane_b32 s3, v252, 7
	s_nop 4
	global_load_dword v1, v113, s[2:3] sc1
	v_readlane_b32 s2, v252, 8
	v_readlane_b32 s3, v252, 9
	s_nop 4
	global_load_dword v2, v113, s[2:3] sc1
	v_readlane_b32 s2, v252, 10
	v_readlane_b32 s3, v252, 11
	s_nop 4
	global_load_dword v3, v113, s[2:3] sc1
	v_readlane_b32 s2, v252, 12
	v_readlane_b32 s3, v252, 13
	s_nop 4
	global_load_dword v4, v113, s[2:3] sc1
	v_readlane_b32 s2, v252, 14
	v_readlane_b32 s3, v252, 15
	s_nop 4
	global_load_dword v5, v113, s[2:3] sc1
	v_readlane_b32 s2, v252, 16
	v_readlane_b32 s3, v252, 17
	s_nop 4
	global_load_dword v6, v113, s[2:3] sc1
	v_readlane_b32 s2, v252, 18
	v_readlane_b32 s3, v252, 19
	s_nop 4
	global_load_dword v7, v113, s[2:3] sc1
	v_readlane_b32 s2, v252, 20
	v_readlane_b32 s3, v252, 21
	s_nop 4
	global_load_dword v8, v113, s[2:3] sc1
	v_readlane_b32 s2, v252, 22
	v_readlane_b32 s3, v252, 23
	s_nop 4
	global_load_dword v9, v113, s[2:3] sc1
	v_readlane_b32 s2, v252, 24
	v_readlane_b32 s3, v252, 25
	s_nop 4
	global_load_dword v10, v113, s[2:3] sc1
	v_readlane_b32 s2, v252, 26
	v_readlane_b32 s3, v252, 27
	s_nop 4
	global_load_dword v11, v113, s[2:3] sc1
	v_readlane_b32 s2, v252, 28
	v_readlane_b32 s3, v252, 29
	s_nop 4
	global_load_dword v12, v113, s[2:3] sc1
	v_readlane_b32 s2, v252, 30
	v_readlane_b32 s3, v252, 31
	s_nop 4
	global_load_dword v13, v113, s[2:3] sc1
	v_readlane_b32 s2, v252, 32
	v_readlane_b32 s3, v252, 33
	s_nop 4
	global_load_dword v14, v113, s[2:3] sc1
	v_readlane_b32 s2, v252, 34
	v_readlane_b32 s3, v252, 35
	s_nop 4
	global_load_dword v15, v113, s[2:3] sc1
	s_mov_b64 s[2:3], -1
	s_waitcnt vmcnt(0)
	v_add_u32_e32 v16, v1, v0
	v_add_u32_e32 v16, v16, v2
	v_add_u32_e32 v16, v16, v3
	v_add_u32_e32 v16, v16, v4
	v_add_u32_e32 v16, v16, v5
	v_add_u32_e32 v16, v16, v6
	v_add_u32_e32 v16, v16, v7
	v_add_u32_e32 v16, v16, v8
	v_add_u32_e32 v16, v16, v9
	v_add_u32_e32 v16, v16, v10
	v_add_u32_e32 v16, v16, v11
	v_add_u32_e32 v16, v16, v12
	v_add_u32_e32 v16, v16, v13
	v_add_u32_e32 v16, v16, v14
	v_add_u32_e32 v16, v16, v15
	v_cmp_eq_u32_e32 vcc, s4, v16
	s_mov_b64 s[4:5], -1
	s_cbranch_vccnz .LBB0_97
	s_and_b32 s2, s8, 0xff
	s_cmp_eq_u32 s2, 0
	s_mov_b64 s[2:3], -1
	s_mov_b64 s[6:7], -1
	s_sleep 1
	s_cbranch_scc0 .LBB0_102
	v_readlane_b32 s2, v252, 2
	v_readlane_b32 s3, v252, 3
	s_nop 4
	global_load_dword v16, v113, s[2:3] sc1
	s_waitcnt vmcnt(0)
	v_cmp_eq_u32_e32 vcc, 0, v16
	s_cbranch_vccnz .LBB0_104
	s_mov_b64 s[6:7], 0
	s_mov_b64 s[2:3], -1
